# P2 and P6 GEMM loops: first k-iteration peeled with accumulators fed from inline 0, the 128 zeroing v_mov per unit removed
# speedup vs baseline: 1.0009x; 1.0009x over previous
; #define PG8_STAGE(bufoff, gbase, voff) do { _Pragma("unroll") for (int _i = 0; _i < 2; ++_i) \
;         __builtin_amdgcn_global_load_lds((const unsigned*)((const char*)(gbase) + (voff)[_i]), (LAS unsigned*)(lds + (bufoff) + ldsw + _i * 8192), 16, 0, 0); } while (0)
; #define PG8_LDA(dst, b, h) do { _Pragma("unroll") for (int m = 0; m < 4; ++m) _Pragma("unroll") for (int k = 0; k < 2; ++k) dst[m][k] = *(const LAS bf16x8*)(lds + PG8_SA(b, h) + aoff + m * 2048 + k * 1024); } while (0)
; #define PG8_LDB(dst, b, h) do { _Pragma("unroll") for (int n = 0; n < 2; ++n) _Pragma("unroll") for (int k = 0; k < 2; ++k) dst[n][k] = *(const LAS bf16x8*)(lds + PG8_SB(b, h) + boff + n * 2048 + k * 1024); } while (0)
; #define PG8_MMA(ai, bj, At, Bt) do { __builtin_amdgcn_s_setprio(1); _Pragma("unroll") for (int m = 0; m < 4; ++m) _Pragma("unroll") for (int n = 0; n < 2; ++n) _Pragma("unroll") for (int k = 0; k < 2; ++k) \
;         acc[ai][bj][m][n] = __builtin_amdgcn_mfma_f32_16x16x32_bf16(Bt[n][k], At[m][k], acc[ai][bj][m][n], 0, 0, 0); __builtin_amdgcn_s_setprio(0); } while (0)
; #define PG8_WAIT_V(n) asm volatile("s_waitcnt vmcnt(" #n ")" ::: "memory")
; #define PG8_WAIT_L(n) asm volatile("s_waitcnt lgkmcnt(" #n ")" ::: "memory")
; #define PG8_BAR __builtin_amdgcn_s_barrier()
; #define PG8_SCHED __builtin_amdgcn_sched_barrier(0)
; template <class Epi, bool ALIGN_EPI, bool SP2>
; __device__ __forceinline__ void gemm_phase(LAS unsigned char* lds, const Sched2& S, const Epi& E) {
;     ...
;             PG8_LDB(B0, 0, 0); PG8_LDB(B1, 0, 1); PG8_SCHED; PG8_LDA(At, 0, 0); PG8_STAGE(PG8_SA(1, 1), a1 + hstep, voffA);
;             PG8_WAIT_V(8); PG8_WAIT_L(0); PG8_BAR; PG8_MMA(0, 0, At, B0); PG8_MMA(0, 1, At, B1); PG8_BAR; PG8_SCHED;
;             PG8_LDA(At, 0, 1); PG8_STAGE(PG8_SB(0, 0), b2, voffB); PG8_STAGE(PG8_SB(0, 1), b2 + hstep, voffB); PG8_STAGE(PG8_SA(0, 0), a2, voffA);
;             PG8_WAIT_V(8); PG8_WAIT_L(0); PG8_BAR; PG8_MMA(1, 0, At, B0); PG8_MMA(1, 1, At, B1); PG8_BAR; PG8_SCHED;
;     ...
;         for (int a = 0; a < 2; ++a)
; #pragma unroll
;             for (int b = 0; b < 2; ++b)
; #pragma unroll
;                 for (int m = 0; m < 4; ++m)
; #pragma unroll
;                     for (int n = 0; n < 2; ++n) acc[a][b][m][n] = (f32x4){0.f, 0.f, 0.f, 0.f};
.LBB0_189:
	s_ashr_i32 s41, s40, 31
	s_lshl_b64 s[58:59], s[40:41], 19
	s_add_u32 s1, s6, s58
	s_addc_u32 s41, s7, s59
	s_and_b64 s[58:59], s[48:49], exec
	s_cselect_b32 s65, s41, s73
	s_cselect_b32 s64, s1, s72
	s_ashr_i32 s43, s42, 31
	s_lshl_b64 s[58:59], s[42:43], 19
	s_add_u32 s1, s62, s58
	s_addc_u32 s41, s63, s59
	s_and_b64 s[58:59], s[48:49], exec
	s_cselect_b32 s69, s41, s75
	s_cselect_b32 s68, s1, s74
	s_add_u32 s72, s72, 0x40080
	s_addc_u32 s73, s73, 0
	s_add_u32 s1, s74, 0x100
	s_addc_u32 s41, s75, 0
	s_mov_b32 s43, -2
	ds_read_b128 v[144:147], v158
	ds_read_b128 v[148:151], v158 offset:1024
	ds_read_b128 v[162:165], v158 offset:2048
	ds_read_b128 v[166:169], v158 offset:3072
	ds_read_b128 v[170:173], v159
	ds_read_b128 v[174:177], v159 offset:1024
	ds_read_b128 v[178:181], v159 offset:2048
	ds_read_b128 v[182:185], v159 offset:3072
	s_add_u32 s58, s72, 0xfffc0080
	s_addc_u32 s59, s73, -1
	s_cmp_eq_u32 s43, 12
	s_cselect_b32 s77, s65, s59
	s_cselect_b32 s76, s64, s58
	s_cselect_b32 s75, s69, s41
	s_cselect_b32 s74, s68, s1
	v_lshl_add_u64 v[152:153], s[72:73], 0, v[140:141]
	s_add_i32 m0, s67, 0xc000
	ds_read_b128 v[186:189], v160
	ds_read_b128 v[190:193], v160 offset:1024
	ds_read_b128 v[194:197], v160 offset:2048
	ds_read_b128 v[198:201], v160 offset:3072
	ds_read_b128 v[202:205], v160 offset:4096
	ds_read_b128 v[206:209], v160 offset:5120
	ds_read_b128 v[210:213], v160 offset:6144
	ds_read_b128 v[214:217], v160 offset:7168
	global_load_lds_dwordx4 v[152:153], off
	v_lshl_add_u64 v[152:153], s[72:73], 0, v[142:143]
	s_add_i32 m0, s67, 0xe000
	s_nop 0
	global_load_lds_dwordx4 v[152:153], off
	s_waitcnt vmcnt(8)
	s_waitcnt lgkmcnt(0)
	s_barrier
	s_setprio 1
	s_waitcnt lgkmcnt(0)
	v_mfma_f32_16x16x32_bf16 v[126:129], v[144:147], v[186:189], 0
	v_mfma_f32_16x16x32_bf16 v[122:125], v[162:165], v[186:189], 0
	v_mfma_f32_16x16x32_bf16 v[110:113], v[144:147], v[194:197], 0
	v_mfma_f32_16x16x32_bf16 v[106:109], v[162:165], v[194:197], 0
	v_mfma_f32_16x16x32_bf16 v[94:97], v[144:147], v[202:205], 0
	v_mfma_f32_16x16x32_bf16 v[90:93], v[162:165], v[202:205], 0
	v_mfma_f32_16x16x32_bf16 v[78:81], v[144:147], v[210:213], 0
	v_mfma_f32_16x16x32_bf16 v[74:77], v[162:165], v[210:213], 0
	v_mfma_f32_16x16x32_bf16 v[126:129], v[148:151], v[190:193], v[126:129]
	v_mfma_f32_16x16x32_bf16 v[122:125], v[166:169], v[190:193], v[122:125]
	v_mfma_f32_16x16x32_bf16 v[110:113], v[148:151], v[198:201], v[110:113]
	v_mfma_f32_16x16x32_bf16 v[106:109], v[166:169], v[198:201], v[106:109]
	v_mfma_f32_16x16x32_bf16 v[94:97], v[148:151], v[206:209], v[94:97]
	v_mfma_f32_16x16x32_bf16 v[90:93], v[166:169], v[206:209], v[90:93]
	v_mfma_f32_16x16x32_bf16 v[78:81], v[148:151], v[214:217], v[78:81]
	v_mfma_f32_16x16x32_bf16 v[74:77], v[166:169], v[214:217], v[74:77]
	s_setprio 0
	s_setprio 1
	v_mfma_f32_16x16x32_bf16 v[118:121], v[170:173], v[186:189], 0
	v_mfma_f32_16x16x32_bf16 v[114:117], v[178:181], v[186:189], 0
	v_mfma_f32_16x16x32_bf16 v[102:105], v[170:173], v[194:197], 0
	v_mfma_f32_16x16x32_bf16 v[98:101], v[178:181], v[194:197], 0
	v_mfma_f32_16x16x32_bf16 v[86:89], v[170:173], v[202:205], 0
	v_mfma_f32_16x16x32_bf16 v[82:85], v[178:181], v[202:205], 0
	v_mfma_f32_16x16x32_bf16 v[70:73], v[170:173], v[210:213], 0
	v_mfma_f32_16x16x32_bf16 v[66:69], v[178:181], v[210:213], 0
	v_mfma_f32_16x16x32_bf16 v[118:121], v[174:177], v[190:193], v[118:121]
	v_mfma_f32_16x16x32_bf16 v[114:117], v[182:185], v[190:193], v[114:117]
	v_mfma_f32_16x16x32_bf16 v[102:105], v[174:177], v[198:201], v[102:105]
	v_mfma_f32_16x16x32_bf16 v[98:101], v[182:185], v[198:201], v[98:101]
	v_mfma_f32_16x16x32_bf16 v[86:89], v[174:177], v[206:209], v[86:89]
	v_mfma_f32_16x16x32_bf16 v[82:85], v[182:185], v[206:209], v[82:85]
	v_mfma_f32_16x16x32_bf16 v[70:73], v[174:177], v[214:217], v[70:73]
	v_mfma_f32_16x16x32_bf16 v[66:69], v[182:185], v[214:217], v[66:69]
	s_setprio 0
	s_barrier
	s_add_i32 s58, s88, s35
	v_lshl_add_u64 v[152:153], s[74:75], 0, v[132:133]
	s_mov_b32 m0, s58
	ds_read_b128 v[186:189], v160 offset:16384
	ds_read_b128 v[190:193], v160 offset:17408
	ds_read_b128 v[194:197], v160 offset:18432
	ds_read_b128 v[198:201], v160 offset:19456
	ds_read_b128 v[202:205], v160 offset:20480
	ds_read_b128 v[206:209], v160 offset:21504
	ds_read_b128 v[210:213], v160 offset:22528
	ds_read_b128 v[214:217], v160 offset:23552
	global_load_lds_dwordx4 v[152:153], off
	s_add_i32 m0, s58, 0x2000
	s_add_u32 s58, s74, 0x40000
	v_lshl_add_u64 v[218:219], s[74:75], 0, v[136:137]
	s_addc_u32 s59, s75, 0
	s_add_i32 s71, s89, s35
	global_load_lds_dwordx4 v[218:219], off
	v_lshl_add_u64 v[220:221], s[58:59], 0, v[132:133]
	s_mov_b32 m0, s71
	v_lshl_add_u64 v[222:223], s[76:77], 0, v[134:135]
	global_load_lds_dwordx4 v[220:221], off
	v_lshl_add_u64 v[220:221], s[58:59], 0, v[136:137]
	s_add_i32 m0, s71, 0x2000
	s_nop 0
	global_load_lds_dwordx4 v[220:221], off
	v_lshl_add_u64 v[220:221], s[76:77], 0, v[130:131]
	s_mov_b32 m0, s67
	s_nop 0
	global_load_lds_dwordx4 v[220:221], off
	s_mov_b32 m0, s80
	s_nop 0
	global_load_lds_dwordx4 v[222:223], off
	s_waitcnt vmcnt(8)
	s_waitcnt lgkmcnt(0)
	s_barrier
; #define PG8_STAGE(bufoff, gbase, voff) do { _Pragma("unroll") for (int _i = 0; _i < 2; ++_i) \
;         __builtin_amdgcn_global_load_lds((const unsigned*)((const char*)(gbase) + (voff)[_i]), (LAS unsigned*)(lds + (bufoff) + ldsw + _i * 8192), 16, 0, 0); } while (0)
; #define PG8_LDA(dst, b, h) do { _Pragma("unroll") for (int m = 0; m < 4; ++m) _Pragma("unroll") for (int k = 0; k < 2; ++k) dst[m][k] = *(const LAS bf16x8*)(lds + PG8_SA(b, h) + aoff + m * 2048 + k * 1024); } while (0)
; #define PG8_LDB(dst, b, h) do { _Pragma("unroll") for (int n = 0; n < 2; ++n) _Pragma("unroll") for (int k = 0; k < 2; ++k) dst[n][k] = *(const LAS bf16x8*)(lds + PG8_SB(b, h) + boff + n * 2048 + k * 1024); } while (0)
; #define PG8_MMA(ai, bj, At, Bt) do { __builtin_amdgcn_s_setprio(1); _Pragma("unroll") for (int m = 0; m < 4; ++m) _Pragma("unroll") for (int n = 0; n < 2; ++n) _Pragma("unroll") for (int k = 0; k < 2; ++k) \
;         acc[ai][bj][m][n] = __builtin_amdgcn_mfma_f32_16x16x32_bf16(Bt[n][k], At[m][k], acc[ai][bj][m][n], 0, 0, 0); __builtin_amdgcn_s_setprio(0); } while (0)
; #define PG8_WAIT_V(n) asm volatile("s_waitcnt vmcnt(" #n ")" ::: "memory")
; #define PG8_WAIT_L(n) asm volatile("s_waitcnt lgkmcnt(" #n ")" ::: "memory")
; #define PG8_BAR __builtin_amdgcn_s_barrier()
; #define PG8_SCHED __builtin_amdgcn_sched_barrier(0)
; template <class Epi, bool ALIGN_EPI, bool SP2>
; __device__ __forceinline__ void gemm_phase(LAS unsigned char* lds, const Sched2& S, const Epi& E) {
;     ...
;             PG8_WAIT_V(8); PG8_WAIT_L(0); PG8_BAR; PG8_MMA(1, 0, At, B0); PG8_MMA(1, 1, At, B1); PG8_BAR; PG8_SCHED;
;             PG8_LDB(B0, 1, 0); PG8_LDB(B1, 1, 1); PG8_SCHED; PG8_LDA(At, 1, 0); PG8_STAGE(PG8_SA(0, 1), a2 + hstep, voffA);
;             PG8_WAIT_V(8); PG8_WAIT_L(0); PG8_BAR; PG8_MMA(0, 0, At, B0); PG8_MMA(0, 1, At, B1); PG8_BAR; PG8_SCHED;
	s_setprio 1
	s_waitcnt lgkmcnt(0)
	v_mfma_f32_16x16x32_bf16 v[62:65], v[144:147], v[186:189], 0
	v_mfma_f32_16x16x32_bf16 v[58:61], v[162:165], v[186:189], 0
	v_mfma_f32_16x16x32_bf16 v[46:49], v[144:147], v[194:197], 0
	v_mfma_f32_16x16x32_bf16 v[42:45], v[162:165], v[194:197], 0
	v_mfma_f32_16x16x32_bf16 v[30:33], v[144:147], v[202:205], 0
	v_mfma_f32_16x16x32_bf16 v[26:29], v[162:165], v[202:205], 0
	v_mfma_f32_16x16x32_bf16 v[14:17], v[144:147], v[210:213], 0
	v_mfma_f32_16x16x32_bf16 v[10:13], v[162:165], v[210:213], 0
	v_mfma_f32_16x16x32_bf16 v[62:65], v[148:151], v[190:193], v[62:65]
	v_mfma_f32_16x16x32_bf16 v[58:61], v[166:169], v[190:193], v[58:61]
	v_mfma_f32_16x16x32_bf16 v[46:49], v[148:151], v[198:201], v[46:49]
	v_mfma_f32_16x16x32_bf16 v[42:45], v[166:169], v[198:201], v[42:45]
	v_mfma_f32_16x16x32_bf16 v[30:33], v[148:151], v[206:209], v[30:33]
	v_mfma_f32_16x16x32_bf16 v[26:29], v[166:169], v[206:209], v[26:29]
	v_mfma_f32_16x16x32_bf16 v[14:17], v[148:151], v[214:217], v[14:17]
	v_mfma_f32_16x16x32_bf16 v[10:13], v[166:169], v[214:217], v[10:13]
	s_setprio 0
	s_setprio 1
	v_mfma_f32_16x16x32_bf16 v[54:57], v[170:173], v[186:189], 0
	v_mfma_f32_16x16x32_bf16 v[50:53], v[178:181], v[186:189], 0
	v_mfma_f32_16x16x32_bf16 v[38:41], v[170:173], v[194:197], 0
	v_mfma_f32_16x16x32_bf16 v[34:37], v[178:181], v[194:197], 0
	v_mfma_f32_16x16x32_bf16 v[22:25], v[170:173], v[202:205], 0
	v_mfma_f32_16x16x32_bf16 v[18:21], v[178:181], v[202:205], 0
	v_mfma_f32_16x16x32_bf16 v[6:9], v[170:173], v[210:213], 0
	v_mfma_f32_16x16x32_bf16 v[2:5], v[178:181], v[210:213], 0
	v_mfma_f32_16x16x32_bf16 v[54:57], v[174:177], v[190:193], v[54:57]
	v_mfma_f32_16x16x32_bf16 v[50:53], v[182:185], v[190:193], v[50:53]
	v_mfma_f32_16x16x32_bf16 v[38:41], v[174:177], v[198:201], v[38:41]
	v_mfma_f32_16x16x32_bf16 v[34:37], v[182:185], v[198:201], v[34:37]
	v_mfma_f32_16x16x32_bf16 v[22:25], v[174:177], v[206:209], v[22:25]
	v_mfma_f32_16x16x32_bf16 v[18:21], v[182:185], v[206:209], v[18:21]
	v_mfma_f32_16x16x32_bf16 v[6:9], v[174:177], v[214:217], v[6:9]
	v_mfma_f32_16x16x32_bf16 v[2:5], v[182:185], v[214:217], v[2:5]
	s_setprio 0
	s_barrier
	s_add_i32 s71, 0, 0x18000
	v_add_u32_e32 v138, s71, v155
	s_add_i32 s94, 0, 0x1c000
	ds_read_b128 v[144:147], v138
	ds_read_b128 v[148:151], v138 offset:1024
	ds_read_b128 v[162:165], v138 offset:2048
	ds_read_b128 v[166:169], v138 offset:3072
	v_add_u32_e32 v138, s94, v155
	ds_read_b128 v[170:173], v138
	ds_read_b128 v[174:177], v138 offset:1024
	ds_read_b128 v[178:181], v138 offset:2048
	ds_read_b128 v[182:185], v138 offset:3072
	s_add_u32 s58, s76, 0x40000
	s_addc_u32 s59, s77, 0
	s_mov_b32 m0, s81
	v_lshl_add_u64 v[224:225], s[58:59], 0, v[130:131]
	ds_read_b128 v[186:189], v160 offset:32768
	ds_read_b128 v[190:193], v160 offset:33792
	ds_read_b128 v[194:197], v160 offset:34816
	ds_read_b128 v[198:201], v160 offset:35840
	ds_read_b128 v[202:205], v160 offset:36864
	ds_read_b128 v[206:209], v160 offset:37888
	ds_read_b128 v[210:213], v160 offset:38912
	ds_read_b128 v[214:217], v160 offset:39936
	global_load_lds_dwordx4 v[224:225], off
	v_lshl_add_u64 v[224:225], s[58:59], 0, v[134:135]
	s_mov_b32 m0, s82
	s_nop 0
	global_load_lds_dwordx4 v[224:225], off
	s_waitcnt vmcnt(8)
	s_waitcnt lgkmcnt(0)
	s_barrier
	s_setprio 1
	s_waitcnt lgkmcnt(0)
	v_mfma_f32_16x16x32_bf16 v[126:129], v[144:147], v[186:189], v[126:129]
	v_mfma_f32_16x16x32_bf16 v[122:125], v[162:165], v[186:189], v[122:125]
	v_mfma_f32_16x16x32_bf16 v[110:113], v[144:147], v[194:197], v[110:113]
	v_mfma_f32_16x16x32_bf16 v[106:109], v[162:165], v[194:197], v[106:109]
	v_mfma_f32_16x16x32_bf16 v[94:97], v[144:147], v[202:205], v[94:97]
	v_mfma_f32_16x16x32_bf16 v[90:93], v[162:165], v[202:205], v[90:93]
	v_mfma_f32_16x16x32_bf16 v[78:81], v[144:147], v[210:213], v[78:81]
	v_mfma_f32_16x16x32_bf16 v[74:77], v[162:165], v[210:213], v[74:77]
	v_mfma_f32_16x16x32_bf16 v[126:129], v[148:151], v[190:193], v[126:129]
	v_mfma_f32_16x16x32_bf16 v[122:125], v[166:169], v[190:193], v[122:125]
	v_mfma_f32_16x16x32_bf16 v[110:113], v[148:151], v[198:201], v[110:113]
	v_mfma_f32_16x16x32_bf16 v[106:109], v[166:169], v[198:201], v[106:109]
	v_mfma_f32_16x16x32_bf16 v[94:97], v[148:151], v[206:209], v[94:97]
	v_mfma_f32_16x16x32_bf16 v[90:93], v[166:169], v[206:209], v[90:93]
	v_mfma_f32_16x16x32_bf16 v[78:81], v[148:151], v[214:217], v[78:81]
	v_mfma_f32_16x16x32_bf16 v[74:77], v[166:169], v[214:217], v[74:77]
	s_setprio 0
	s_setprio 1
	v_mfma_f32_16x16x32_bf16 v[118:121], v[170:173], v[186:189], v[118:121]
	v_mfma_f32_16x16x32_bf16 v[114:117], v[178:181], v[186:189], v[114:117]
	v_mfma_f32_16x16x32_bf16 v[102:105], v[170:173], v[194:197], v[102:105]
	v_mfma_f32_16x16x32_bf16 v[98:101], v[178:181], v[194:197], v[98:101]
	v_mfma_f32_16x16x32_bf16 v[86:89], v[170:173], v[202:205], v[86:89]
	v_mfma_f32_16x16x32_bf16 v[82:85], v[178:181], v[202:205], v[82:85]
	v_mfma_f32_16x16x32_bf16 v[70:73], v[170:173], v[210:213], v[70:73]
	v_mfma_f32_16x16x32_bf16 v[66:69], v[178:181], v[210:213], v[66:69]
	v_mfma_f32_16x16x32_bf16 v[118:121], v[174:177], v[190:193], v[118:121]
	v_mfma_f32_16x16x32_bf16 v[114:117], v[182:185], v[190:193], v[114:117]
	v_mfma_f32_16x16x32_bf16 v[102:105], v[174:177], v[198:201], v[102:105]
	v_mfma_f32_16x16x32_bf16 v[98:101], v[182:185], v[198:201], v[98:101]
	v_mfma_f32_16x16x32_bf16 v[86:89], v[174:177], v[206:209], v[86:89]
	v_mfma_f32_16x16x32_bf16 v[82:85], v[182:185], v[206:209], v[82:85]
	v_mfma_f32_16x16x32_bf16 v[70:73], v[174:177], v[214:217], v[70:73]
	v_mfma_f32_16x16x32_bf16 v[66:69], v[182:185], v[214:217], v[66:69]
	s_setprio 0
	s_barrier
; #define PG8_STAGE(bufoff, gbase, voff) do { _Pragma("unroll") for (int _i = 0; _i < 2; ++_i) \
;         __builtin_amdgcn_global_load_lds((const unsigned*)((const char*)(gbase) + (voff)[_i]), (LAS unsigned*)(lds + (bufoff) + ldsw + _i * 8192), 16, 0, 0); } while (0)
; #define PG8_LDA(dst, b, h) do { _Pragma("unroll") for (int m = 0; m < 4; ++m) _Pragma("unroll") for (int k = 0; k < 2; ++k) dst[m][k] = *(const LAS bf16x8*)(lds + PG8_SA(b, h) + aoff + m * 2048 + k * 1024); } while (0)
; #define PG8_MMA(ai, bj, At, Bt) do { __builtin_amdgcn_s_setprio(1); _Pragma("unroll") for (int m = 0; m < 4; ++m) _Pragma("unroll") for (int n = 0; n < 2; ++n) _Pragma("unroll") for (int k = 0; k < 2; ++k) \
;         acc[ai][bj][m][n] = __builtin_amdgcn_mfma_f32_16x16x32_bf16(Bt[n][k], At[m][k], acc[ai][bj][m][n], 0, 0, 0); __builtin_amdgcn_s_setprio(0); } while (0)
; #define PG8_WAIT_V(n) asm volatile("s_waitcnt vmcnt(" #n ")" ::: "memory")
; #define PG8_WAIT_L(n) asm volatile("s_waitcnt lgkmcnt(" #n ")" ::: "memory")
; #define PG8_BAR __builtin_amdgcn_s_barrier()
; #define PG8_SCHED __builtin_amdgcn_sched_barrier(0)
; template <class Epi, bool ALIGN_EPI, bool SP2>
; __device__ __forceinline__ void gemm_phase(LAS unsigned char* lds, const Sched2& S, const Epi& E) {
;     ...
;         for (int t = 0; t < nt; t += 2) {
;     ...
;             PG8_LDA(At, 1, 1); PG8_STAGE(PG8_SB(1, 0), b3, voffB); PG8_STAGE(PG8_SB(1, 1), b3 + hstep, voffB); PG8_STAGE(PG8_SA(1, 0), a3, voffA);
;             PG8_WAIT_V(8); PG8_WAIT_L(0); PG8_BAR; PG8_MMA(1, 0, At, B0); PG8_MMA(1, 1, At, B1); PG8_BAR; PG8_SCHED;
	s_add_i32 s58, s71, s35
	v_lshl_add_u64 v[152:153], v[152:153], 0, s[18:19]
	s_mov_b32 m0, s58
	ds_read_b128 v[186:189], v160 offset:49152
	ds_read_b128 v[190:193], v160 offset:50176
	ds_read_b128 v[194:197], v160 offset:51200
	ds_read_b128 v[198:201], v160 offset:52224
	ds_read_b128 v[202:205], v160 offset:53248
	ds_read_b128 v[206:209], v160 offset:54272
	ds_read_b128 v[210:213], v160 offset:55296
	ds_read_b128 v[214:217], v160 offset:56320
	global_load_lds_dwordx4 v[152:153], off
	s_add_i32 m0, s58, 0x2000
	s_add_u32 s58, s74, 0x40080
	v_lshl_add_u64 v[152:153], v[218:219], 0, s[18:19]
	s_addc_u32 s59, s75, 0
	s_add_i32 s71, s94, s35
	global_load_lds_dwordx4 v[152:153], off
	v_lshl_add_u64 v[152:153], s[58:59], 0, v[132:133]
	s_mov_b32 m0, s71
	s_nop 0
	global_load_lds_dwordx4 v[152:153], off
	v_lshl_add_u64 v[152:153], s[58:59], 0, v[136:137]
	s_add_i32 m0, s71, 0x2000
	s_nop 0
	global_load_lds_dwordx4 v[152:153], off
	v_lshl_add_u64 v[152:153], v[220:221], 0, s[18:19]
	s_mov_b32 m0, s85
	s_nop 0
	global_load_lds_dwordx4 v[152:153], off
	v_lshl_add_u64 v[152:153], v[222:223], 0, s[18:19]
	s_mov_b32 m0, s86
	s_nop 0
	global_load_lds_dwordx4 v[152:153], off
	s_waitcnt vmcnt(8)
	s_waitcnt lgkmcnt(0)
	s_barrier
	s_setprio 1
	s_waitcnt lgkmcnt(0)
	v_mfma_f32_16x16x32_bf16 v[62:65], v[144:147], v[186:189], v[62:65]
	v_mfma_f32_16x16x32_bf16 v[58:61], v[162:165], v[186:189], v[58:61]
	v_mfma_f32_16x16x32_bf16 v[46:49], v[144:147], v[194:197], v[46:49]
	v_mfma_f32_16x16x32_bf16 v[42:45], v[162:165], v[194:197], v[42:45]
	v_mfma_f32_16x16x32_bf16 v[30:33], v[144:147], v[202:205], v[30:33]
	v_mfma_f32_16x16x32_bf16 v[26:29], v[162:165], v[202:205], v[26:29]
	v_mfma_f32_16x16x32_bf16 v[14:17], v[144:147], v[210:213], v[14:17]
	v_mfma_f32_16x16x32_bf16 v[10:13], v[162:165], v[210:213], v[10:13]
	v_mfma_f32_16x16x32_bf16 v[62:65], v[148:151], v[190:193], v[62:65]
	v_mfma_f32_16x16x32_bf16 v[58:61], v[166:169], v[190:193], v[58:61]
	v_mfma_f32_16x16x32_bf16 v[46:49], v[148:151], v[198:201], v[46:49]
	v_mfma_f32_16x16x32_bf16 v[42:45], v[166:169], v[198:201], v[42:45]
	v_mfma_f32_16x16x32_bf16 v[30:33], v[148:151], v[206:209], v[30:33]
	v_mfma_f32_16x16x32_bf16 v[26:29], v[166:169], v[206:209], v[26:29]
	v_mfma_f32_16x16x32_bf16 v[14:17], v[148:151], v[214:217], v[14:17]
	v_mfma_f32_16x16x32_bf16 v[10:13], v[166:169], v[214:217], v[10:13]
	s_setprio 0
	s_setprio 1
	v_mfma_f32_16x16x32_bf16 v[54:57], v[170:173], v[186:189], v[54:57]
	v_mfma_f32_16x16x32_bf16 v[50:53], v[178:181], v[186:189], v[50:53]
	v_mfma_f32_16x16x32_bf16 v[38:41], v[170:173], v[194:197], v[38:41]
	v_mfma_f32_16x16x32_bf16 v[34:37], v[178:181], v[194:197], v[34:37]
	v_mfma_f32_16x16x32_bf16 v[22:25], v[170:173], v[202:205], v[22:25]
	v_mfma_f32_16x16x32_bf16 v[18:21], v[178:181], v[202:205], v[18:21]
	v_mfma_f32_16x16x32_bf16 v[6:9], v[170:173], v[210:213], v[6:9]
	v_mfma_f32_16x16x32_bf16 v[2:5], v[178:181], v[210:213], v[2:5]
	v_mfma_f32_16x16x32_bf16 v[54:57], v[174:177], v[190:193], v[54:57]
	v_mfma_f32_16x16x32_bf16 v[50:53], v[182:185], v[190:193], v[50:53]
	v_mfma_f32_16x16x32_bf16 v[38:41], v[174:177], v[198:201], v[38:41]
	v_mfma_f32_16x16x32_bf16 v[34:37], v[182:185], v[198:201], v[34:37]
	v_mfma_f32_16x16x32_bf16 v[22:25], v[174:177], v[206:209], v[22:25]
	v_mfma_f32_16x16x32_bf16 v[18:21], v[182:185], v[206:209], v[18:21]
	v_mfma_f32_16x16x32_bf16 v[6:9], v[174:177], v[214:217], v[6:9]
	v_mfma_f32_16x16x32_bf16 v[2:5], v[182:185], v[214:217], v[2:5]
	s_setprio 0
	s_barrier
	s_add_i32 s43, s43, 2
	s_add_u32 s72, s72, 0x100
	s_addc_u32 s73, s73, 0
	s_add_u32 s1, s1, 0x100
	s_addc_u32 s41, s41, 0
	s_cmp_gt_u32 s43, 13

; #define PG8_STAGE(bufoff, gbase, voff) do { _Pragma("unroll") for (int _i = 0; _i < 2; ++_i) \
;         __builtin_amdgcn_global_load_lds((const unsigned*)((const char*)(gbase) + (voff)[_i]), (LAS unsigned*)(lds + (bufoff) + ldsw + _i * 8192), 16, 0, 0); } while (0)
; #define PG8_LDA(dst, b, h) do { _Pragma("unroll") for (int m = 0; m < 4; ++m) _Pragma("unroll") for (int k = 0; k < 2; ++k) dst[m][k] = *(const LAS bf16x8*)(lds + PG8_SA(b, h) + aoff + m * 2048 + k * 1024); } while (0)
; #define PG8_LDB(dst, b, h) do { _Pragma("unroll") for (int n = 0; n < 2; ++n) _Pragma("unroll") for (int k = 0; k < 2; ++k) dst[n][k] = *(const LAS bf16x8*)(lds + PG8_SB(b, h) + boff + n * 2048 + k * 1024); } while (0)
; #define PG8_MMA(ai, bj, At, Bt) do { __builtin_amdgcn_s_setprio(1); _Pragma("unroll") for (int m = 0; m < 4; ++m) _Pragma("unroll") for (int n = 0; n < 2; ++n) _Pragma("unroll") for (int k = 0; k < 2; ++k) \
;         acc[ai][bj][m][n] = __builtin_amdgcn_mfma_f32_16x16x32_bf16(Bt[n][k], At[m][k], acc[ai][bj][m][n], 0, 0, 0); __builtin_amdgcn_s_setprio(0); } while (0)
; #define PG8_WAIT_V(n) asm volatile("s_waitcnt vmcnt(" #n ")" ::: "memory")
; #define PG8_WAIT_L(n) asm volatile("s_waitcnt lgkmcnt(" #n ")" ::: "memory")
; #define PG8_BAR __builtin_amdgcn_s_barrier()
; #define PG8_SCHED __builtin_amdgcn_sched_barrier(0)
; template <class Epi, bool ALIGN_EPI, bool SP2>
; __device__ __forceinline__ void gemm_phase(LAS unsigned char* lds, const Sched2& S, const Epi& E) {
;     ...
;             PG8_LDB(B0, 0, 0); PG8_LDB(B1, 0, 1); PG8_SCHED; PG8_LDA(At, 0, 0); PG8_STAGE(PG8_SA(1, 1), a1 + hstep, voffA);
;             PG8_WAIT_V(8); PG8_WAIT_L(0); PG8_BAR; PG8_MMA(0, 0, At, B0); PG8_MMA(0, 1, At, B1); PG8_BAR; PG8_SCHED;
;             PG8_LDA(At, 0, 1); PG8_STAGE(PG8_SB(0, 0), b2, voffB); PG8_STAGE(PG8_SB(0, 1), b2 + hstep, voffB); PG8_STAGE(PG8_SA(0, 0), a2, voffA);
;             PG8_WAIT_V(8); PG8_WAIT_L(0); PG8_BAR; PG8_MMA(1, 0, At, B0); PG8_MMA(1, 1, At, B1); PG8_BAR; PG8_SCHED;
;     ...
;         for (int a = 0; a < 2; ++a)
; #pragma unroll
;             for (int b = 0; b < 2; ++b)
; #pragma unroll
;                 for (int m = 0; m < 4; ++m)
; #pragma unroll
;                     for (int n = 0; n < 2; ++n) acc[a][b][m][n] = (f32x4){0.f, 0.f, 0.f, 0.f};
.LBB0_470:
	s_add_u32 s36, s36, 0x40080
	s_addc_u32 s37, s37, 0
	s_add_u32 s23, s38, 0x100
	s_addc_u32 s25, s39, 0
	s_mov_b32 s35, -2
	ds_read_b128 v[130:133], v213
	ds_read_b128 v[134:137], v213 offset:1024
	ds_read_b128 v[138:141], v213 offset:2048
	ds_read_b128 v[142:145], v213 offset:3072
	ds_read_b128 v[146:149], v217
	ds_read_b128 v[150:153], v217 offset:1024
	ds_read_b128 v[154:157], v217 offset:2048
	ds_read_b128 v[158:161], v217 offset:3072
	s_add_u32 s38, s36, 0xfffc0080
	s_addc_u32 s39, s37, -1
	s_cmp_eq_u32 s35, 12
	s_cselect_b32 s41, s27, s39
	s_cselect_b32 s40, s26, s38
	s_cselect_b32 s39, s29, s25
	s_cselect_b32 s38, s28, s23
	v_lshl_add_u64 v[202:203], s[36:37], 0, v[174:175]
	s_add_i32 m0, s31, 0xc000
	ds_read_b128 v[178:181], v238
	ds_read_b128 v[182:185], v238 offset:1024
	ds_read_b128 v[186:189], v238 offset:2048
	ds_read_b128 v[190:193], v238 offset:3072
	ds_read_b128 v[218:221], v238 offset:4096
	ds_read_b128 v[222:225], v238 offset:5120
	ds_read_b128 v[226:229], v238 offset:6144
	ds_read_b128 v[230:233], v238 offset:7168
	global_load_lds_dwordx4 v[202:203], off
	v_lshl_add_u64 v[202:203], s[36:37], 0, v[176:177]
	s_add_i32 m0, s31, 0xe000
	s_nop 0
	global_load_lds_dwordx4 v[202:203], off
	s_waitcnt vmcnt(8)
	s_waitcnt lgkmcnt(0)
	s_barrier
	s_setprio 1
	s_waitcnt lgkmcnt(0)
	v_mfma_f32_16x16x32_bf16 v[126:129], v[130:133], v[178:181], 0
	v_mfma_f32_16x16x32_bf16 v[122:125], v[138:141], v[178:181], 0
	v_mfma_f32_16x16x32_bf16 v[110:113], v[130:133], v[186:189], 0
	v_mfma_f32_16x16x32_bf16 v[106:109], v[138:141], v[186:189], 0
	v_mfma_f32_16x16x32_bf16 v[94:97], v[130:133], v[218:221], 0
	v_mfma_f32_16x16x32_bf16 v[90:93], v[138:141], v[218:221], 0
	v_mfma_f32_16x16x32_bf16 v[78:81], v[130:133], v[226:229], 0
	v_mfma_f32_16x16x32_bf16 v[74:77], v[138:141], v[226:229], 0
	v_mfma_f32_16x16x32_bf16 v[126:129], v[134:137], v[182:185], v[126:129]
	v_mfma_f32_16x16x32_bf16 v[122:125], v[142:145], v[182:185], v[122:125]
	v_mfma_f32_16x16x32_bf16 v[110:113], v[134:137], v[190:193], v[110:113]
	v_mfma_f32_16x16x32_bf16 v[106:109], v[142:145], v[190:193], v[106:109]
	v_mfma_f32_16x16x32_bf16 v[94:97], v[134:137], v[222:225], v[94:97]
	v_mfma_f32_16x16x32_bf16 v[90:93], v[142:145], v[222:225], v[90:93]
	v_mfma_f32_16x16x32_bf16 v[78:81], v[134:137], v[230:233], v[78:81]
	v_mfma_f32_16x16x32_bf16 v[74:77], v[142:145], v[230:233], v[74:77]
	s_setprio 0
	s_setprio 1
	v_mfma_f32_16x16x32_bf16 v[118:121], v[146:149], v[178:181], 0
	v_mfma_f32_16x16x32_bf16 v[114:117], v[154:157], v[178:181], 0
	v_mfma_f32_16x16x32_bf16 v[102:105], v[146:149], v[186:189], 0
	v_mfma_f32_16x16x32_bf16 v[98:101], v[154:157], v[186:189], 0
	v_mfma_f32_16x16x32_bf16 v[86:89], v[146:149], v[218:221], 0
	v_mfma_f32_16x16x32_bf16 v[82:85], v[154:157], v[218:221], 0
	v_mfma_f32_16x16x32_bf16 v[70:73], v[146:149], v[226:229], 0
	v_mfma_f32_16x16x32_bf16 v[66:69], v[154:157], v[226:229], 0
	v_mfma_f32_16x16x32_bf16 v[118:121], v[150:153], v[182:185], v[118:121]
	v_mfma_f32_16x16x32_bf16 v[114:117], v[158:161], v[182:185], v[114:117]
	v_mfma_f32_16x16x32_bf16 v[102:105], v[150:153], v[190:193], v[102:105]
	v_mfma_f32_16x16x32_bf16 v[98:101], v[158:161], v[190:193], v[98:101]
	v_mfma_f32_16x16x32_bf16 v[86:89], v[150:153], v[222:225], v[86:89]
	v_mfma_f32_16x16x32_bf16 v[82:85], v[158:161], v[222:225], v[82:85]
	v_mfma_f32_16x16x32_bf16 v[70:73], v[150:153], v[230:233], v[70:73]
	v_mfma_f32_16x16x32_bf16 v[66:69], v[158:161], v[230:233], v[66:69]
	s_setprio 0
	s_barrier
	s_add_i32 s58, s76, s48
	v_lshl_add_u64 v[202:203], s[38:39], 0, v[164:165]
	s_mov_b32 m0, s58
	ds_read_b128 v[178:181], v238 offset:16384
	ds_read_b128 v[182:185], v238 offset:17408
	ds_read_b128 v[186:189], v238 offset:18432
	ds_read_b128 v[190:193], v238 offset:19456
	ds_read_b128 v[218:221], v238 offset:20480
	ds_read_b128 v[222:225], v238 offset:21504
	ds_read_b128 v[226:229], v238 offset:22528
	ds_read_b128 v[230:233], v238 offset:23552
	global_load_lds_dwordx4 v[202:203], off
	s_add_i32 m0, s58, 0x2000
	s_add_u32 s58, s38, 0x40000
	v_lshl_add_u64 v[206:207], s[38:39], 0, v[168:169]
	s_addc_u32 s59, s39, 0
	s_add_i32 s81, s77, s48
	global_load_lds_dwordx4 v[206:207], off
	v_lshl_add_u64 v[210:211], s[58:59], 0, v[164:165]
	s_mov_b32 m0, s81
	v_lshl_add_u64 v[214:215], s[40:41], 0, v[166:167]
	global_load_lds_dwordx4 v[210:211], off
	v_lshl_add_u64 v[210:211], s[58:59], 0, v[168:169]
	s_add_i32 m0, s81, 0x2000
	s_nop 0
	global_load_lds_dwordx4 v[210:211], off
	v_lshl_add_u64 v[210:211], s[40:41], 0, v[162:163]
	s_mov_b32 m0, s31
	s_nop 0
	global_load_lds_dwordx4 v[210:211], off
	s_mov_b32 m0, s49
	s_nop 0
	global_load_lds_dwordx4 v[214:215], off
	s_waitcnt vmcnt(8)
	s_waitcnt lgkmcnt(0)
	s_barrier
; #define PG8_STAGE(bufoff, gbase, voff) do { _Pragma("unroll") for (int _i = 0; _i < 2; ++_i) \
;         __builtin_amdgcn_global_load_lds((const unsigned*)((const char*)(gbase) + (voff)[_i]), (LAS unsigned*)(lds + (bufoff) + ldsw + _i * 8192), 16, 0, 0); } while (0)
; #define PG8_LDA(dst, b, h) do { _Pragma("unroll") for (int m = 0; m < 4; ++m) _Pragma("unroll") for (int k = 0; k < 2; ++k) dst[m][k] = *(const LAS bf16x8*)(lds + PG8_SA(b, h) + aoff + m * 2048 + k * 1024); } while (0)
; #define PG8_LDB(dst, b, h) do { _Pragma("unroll") for (int n = 0; n < 2; ++n) _Pragma("unroll") for (int k = 0; k < 2; ++k) dst[n][k] = *(const LAS bf16x8*)(lds + PG8_SB(b, h) + boff + n * 2048 + k * 1024); } while (0)
; #define PG8_MMA(ai, bj, At, Bt) do { __builtin_amdgcn_s_setprio(1); _Pragma("unroll") for (int m = 0; m < 4; ++m) _Pragma("unroll") for (int n = 0; n < 2; ++n) _Pragma("unroll") for (int k = 0; k < 2; ++k) \
;         acc[ai][bj][m][n] = __builtin_amdgcn_mfma_f32_16x16x32_bf16(Bt[n][k], At[m][k], acc[ai][bj][m][n], 0, 0, 0); __builtin_amdgcn_s_setprio(0); } while (0)
; #define PG8_WAIT_V(n) asm volatile("s_waitcnt vmcnt(" #n ")" ::: "memory")
; #define PG8_WAIT_L(n) asm volatile("s_waitcnt lgkmcnt(" #n ")" ::: "memory")
; #define PG8_BAR __builtin_amdgcn_s_barrier()
; #define PG8_SCHED __builtin_amdgcn_sched_barrier(0)
; template <class Epi, bool ALIGN_EPI, bool SP2>
; __device__ __forceinline__ void gemm_phase(LAS unsigned char* lds, const Sched2& S, const Epi& E) {
;     ...
;             PG8_WAIT_V(8); PG8_WAIT_L(0); PG8_BAR; PG8_MMA(1, 0, At, B0); PG8_MMA(1, 1, At, B1); PG8_BAR; PG8_SCHED;
;             PG8_LDB(B0, 1, 0); PG8_LDB(B1, 1, 1); PG8_SCHED; PG8_LDA(At, 1, 0); PG8_STAGE(PG8_SA(0, 1), a2 + hstep, voffA);
;             PG8_WAIT_V(8); PG8_WAIT_L(0); PG8_BAR; PG8_MMA(0, 0, At, B0); PG8_MMA(0, 1, At, B1); PG8_BAR; PG8_SCHED;
	s_setprio 1
	s_waitcnt lgkmcnt(0)
	v_mfma_f32_16x16x32_bf16 v[62:65], v[130:133], v[178:181], 0
	v_mfma_f32_16x16x32_bf16 v[58:61], v[138:141], v[178:181], 0
	v_mfma_f32_16x16x32_bf16 v[46:49], v[130:133], v[186:189], 0
	v_mfma_f32_16x16x32_bf16 v[42:45], v[138:141], v[186:189], 0
	v_mfma_f32_16x16x32_bf16 v[30:33], v[130:133], v[218:221], 0
	v_mfma_f32_16x16x32_bf16 v[26:29], v[138:141], v[218:221], 0
	v_mfma_f32_16x16x32_bf16 v[22:25], v[130:133], v[226:229], 0
	v_mfma_f32_16x16x32_bf16 v[10:13], v[138:141], v[226:229], 0
	v_mfma_f32_16x16x32_bf16 v[62:65], v[134:137], v[182:185], v[62:65]
	v_mfma_f32_16x16x32_bf16 v[58:61], v[142:145], v[182:185], v[58:61]
	v_mfma_f32_16x16x32_bf16 v[46:49], v[134:137], v[190:193], v[46:49]
	v_mfma_f32_16x16x32_bf16 v[42:45], v[142:145], v[190:193], v[42:45]
	v_mfma_f32_16x16x32_bf16 v[30:33], v[134:137], v[222:225], v[30:33]
	v_mfma_f32_16x16x32_bf16 v[26:29], v[142:145], v[222:225], v[26:29]
	v_mfma_f32_16x16x32_bf16 v[22:25], v[134:137], v[230:233], v[22:25]
	v_mfma_f32_16x16x32_bf16 v[10:13], v[142:145], v[230:233], v[10:13]
	s_setprio 0
	s_setprio 1
	v_mfma_f32_16x16x32_bf16 v[54:57], v[146:149], v[178:181], 0
	v_mfma_f32_16x16x32_bf16 v[50:53], v[154:157], v[178:181], 0
	v_mfma_f32_16x16x32_bf16 v[38:41], v[146:149], v[186:189], 0
	v_mfma_f32_16x16x32_bf16 v[34:37], v[154:157], v[186:189], 0
	v_mfma_f32_16x16x32_bf16 v[18:21], v[146:149], v[218:221], 0
	v_mfma_f32_16x16x32_bf16 v[14:17], v[154:157], v[218:221], 0
	v_mfma_f32_16x16x32_bf16 v[6:9], v[146:149], v[226:229], 0
	v_mfma_f32_16x16x32_bf16 v[2:5], v[154:157], v[226:229], 0
	v_mfma_f32_16x16x32_bf16 v[54:57], v[150:153], v[182:185], v[54:57]
	v_mfma_f32_16x16x32_bf16 v[50:53], v[158:161], v[182:185], v[50:53]
	v_mfma_f32_16x16x32_bf16 v[38:41], v[150:153], v[190:193], v[38:41]
	v_mfma_f32_16x16x32_bf16 v[34:37], v[158:161], v[190:193], v[34:37]
	v_mfma_f32_16x16x32_bf16 v[18:21], v[150:153], v[222:225], v[18:21]
	v_mfma_f32_16x16x32_bf16 v[14:17], v[158:161], v[222:225], v[14:17]
	v_mfma_f32_16x16x32_bf16 v[6:9], v[150:153], v[230:233], v[6:9]
	v_mfma_f32_16x16x32_bf16 v[2:5], v[158:161], v[230:233], v[2:5]
	s_setprio 0
	s_barrier
	s_add_i32 s58, 0, 0x18000
	s_add_i32 s59, 0, 0x1c000
	v_add_u32_e32 v142, s58, v195
	v_add_u32_e32 v158, s59, v195
	ds_read_b128 v[130:133], v142
	ds_read_b128 v[134:137], v142 offset:1024
	ds_read_b128 v[138:141], v142 offset:2048
	ds_read_b128 v[142:145], v142 offset:3072
	ds_read_b128 v[146:149], v158
	ds_read_b128 v[150:153], v158 offset:1024
	ds_read_b128 v[154:157], v158 offset:2048
	ds_read_b128 v[158:161], v158 offset:3072
	s_add_u32 s40, s40, 0x40000
	s_addc_u32 s41, s41, 0
	s_mov_b32 m0, s70
	v_lshl_add_u64 v[234:235], s[40:41], 0, v[162:163]
	ds_read_b128 v[178:181], v238 offset:32768
	ds_read_b128 v[182:185], v238 offset:33792
	ds_read_b128 v[186:189], v238 offset:34816
	ds_read_b128 v[190:193], v238 offset:35840
	ds_read_b128 v[218:221], v238 offset:36864
	ds_read_b128 v[222:225], v238 offset:37888
	ds_read_b128 v[226:229], v238 offset:38912
	ds_read_b128 v[230:233], v238 offset:39936
	global_load_lds_dwordx4 v[234:235], off
	v_lshl_add_u64 v[234:235], s[40:41], 0, v[166:167]
	s_mov_b32 m0, s71
	s_nop 0
	global_load_lds_dwordx4 v[234:235], off
	s_waitcnt vmcnt(8)
	s_waitcnt lgkmcnt(0)
	s_barrier
	s_setprio 1
	s_waitcnt lgkmcnt(0)
	v_mfma_f32_16x16x32_bf16 v[126:129], v[130:133], v[178:181], v[126:129]
	v_mfma_f32_16x16x32_bf16 v[122:125], v[138:141], v[178:181], v[122:125]
	v_mfma_f32_16x16x32_bf16 v[110:113], v[130:133], v[186:189], v[110:113]
	v_mfma_f32_16x16x32_bf16 v[106:109], v[138:141], v[186:189], v[106:109]
	v_mfma_f32_16x16x32_bf16 v[94:97], v[130:133], v[218:221], v[94:97]
	v_mfma_f32_16x16x32_bf16 v[90:93], v[138:141], v[218:221], v[90:93]
	v_mfma_f32_16x16x32_bf16 v[78:81], v[130:133], v[226:229], v[78:81]
	v_mfma_f32_16x16x32_bf16 v[74:77], v[138:141], v[226:229], v[74:77]
	v_mfma_f32_16x16x32_bf16 v[126:129], v[134:137], v[182:185], v[126:129]
	v_mfma_f32_16x16x32_bf16 v[122:125], v[142:145], v[182:185], v[122:125]
	v_mfma_f32_16x16x32_bf16 v[110:113], v[134:137], v[190:193], v[110:113]
	v_mfma_f32_16x16x32_bf16 v[106:109], v[142:145], v[190:193], v[106:109]
	v_mfma_f32_16x16x32_bf16 v[94:97], v[134:137], v[222:225], v[94:97]
	v_mfma_f32_16x16x32_bf16 v[90:93], v[142:145], v[222:225], v[90:93]
	v_mfma_f32_16x16x32_bf16 v[78:81], v[134:137], v[230:233], v[78:81]
	v_mfma_f32_16x16x32_bf16 v[74:77], v[142:145], v[230:233], v[74:77]
	s_setprio 0
	s_setprio 1
	v_mfma_f32_16x16x32_bf16 v[118:121], v[146:149], v[178:181], v[118:121]
	v_mfma_f32_16x16x32_bf16 v[114:117], v[154:157], v[178:181], v[114:117]
	v_mfma_f32_16x16x32_bf16 v[102:105], v[146:149], v[186:189], v[102:105]
	v_mfma_f32_16x16x32_bf16 v[98:101], v[154:157], v[186:189], v[98:101]
	v_mfma_f32_16x16x32_bf16 v[86:89], v[146:149], v[218:221], v[86:89]
	v_mfma_f32_16x16x32_bf16 v[82:85], v[154:157], v[218:221], v[82:85]
	v_mfma_f32_16x16x32_bf16 v[70:73], v[146:149], v[226:229], v[70:73]
	v_mfma_f32_16x16x32_bf16 v[66:69], v[154:157], v[226:229], v[66:69]
	v_mfma_f32_16x16x32_bf16 v[118:121], v[150:153], v[182:185], v[118:121]
	v_mfma_f32_16x16x32_bf16 v[114:117], v[158:161], v[182:185], v[114:117]
	v_mfma_f32_16x16x32_bf16 v[102:105], v[150:153], v[190:193], v[102:105]
	v_mfma_f32_16x16x32_bf16 v[98:101], v[158:161], v[190:193], v[98:101]
	v_mfma_f32_16x16x32_bf16 v[86:89], v[150:153], v[222:225], v[86:89]
	v_mfma_f32_16x16x32_bf16 v[82:85], v[158:161], v[222:225], v[82:85]
	v_mfma_f32_16x16x32_bf16 v[70:73], v[150:153], v[230:233], v[70:73]
	v_mfma_f32_16x16x32_bf16 v[66:69], v[158:161], v[230:233], v[66:69]
	s_setprio 0
	s_barrier
; #define PG8_STAGE(bufoff, gbase, voff) do { _Pragma("unroll") for (int _i = 0; _i < 2; ++_i) \
;         __builtin_amdgcn_global_load_lds((const unsigned*)((const char*)(gbase) + (voff)[_i]), (LAS unsigned*)(lds + (bufoff) + ldsw + _i * 8192), 16, 0, 0); } while (0)
; #define PG8_LDA(dst, b, h) do { _Pragma("unroll") for (int m = 0; m < 4; ++m) _Pragma("unroll") for (int k = 0; k < 2; ++k) dst[m][k] = *(const LAS bf16x8*)(lds + PG8_SA(b, h) + aoff + m * 2048 + k * 1024); } while (0)
; #define PG8_MMA(ai, bj, At, Bt) do { __builtin_amdgcn_s_setprio(1); _Pragma("unroll") for (int m = 0; m < 4; ++m) _Pragma("unroll") for (int n = 0; n < 2; ++n) _Pragma("unroll") for (int k = 0; k < 2; ++k) \
;         acc[ai][bj][m][n] = __builtin_amdgcn_mfma_f32_16x16x32_bf16(Bt[n][k], At[m][k], acc[ai][bj][m][n], 0, 0, 0); __builtin_amdgcn_s_setprio(0); } while (0)
; #define PG8_WAIT_V(n) asm volatile("s_waitcnt vmcnt(" #n ")" ::: "memory")
; #define PG8_WAIT_L(n) asm volatile("s_waitcnt lgkmcnt(" #n ")" ::: "memory")
; #define PG8_BAR __builtin_amdgcn_s_barrier()
; #define PG8_SCHED __builtin_amdgcn_sched_barrier(0)
; template <class Epi, bool ALIGN_EPI, bool SP2>
; __device__ __forceinline__ void gemm_phase(LAS unsigned char* lds, const Sched2& S, const Epi& E) {
;     ...
;         for (int t = 0; t < nt; t += 2) {
;     ...
;             PG8_LDA(At, 1, 1); PG8_STAGE(PG8_SB(1, 0), b3, voffB); PG8_STAGE(PG8_SB(1, 1), b3 + hstep, voffB); PG8_STAGE(PG8_SA(1, 0), a3, voffA);
;             PG8_WAIT_V(8); PG8_WAIT_L(0); PG8_BAR; PG8_MMA(1, 0, At, B0); PG8_MMA(1, 1, At, B1); PG8_BAR; PG8_SCHED;
	s_add_i32 s40, s58, s48
	v_lshl_add_u64 v[202:203], v[202:203], 0, s[16:17]
	s_mov_b32 m0, s40
	ds_read_b128 v[178:181], v238 offset:49152
	ds_read_b128 v[182:185], v238 offset:50176
	ds_read_b128 v[186:189], v238 offset:51200
	ds_read_b128 v[190:193], v238 offset:52224
	ds_read_b128 v[218:221], v238 offset:53248
	ds_read_b128 v[222:225], v238 offset:54272
	ds_read_b128 v[226:229], v238 offset:55296
	ds_read_b128 v[230:233], v238 offset:56320
	global_load_lds_dwordx4 v[202:203], off
	s_add_i32 m0, s40, 0x2000
	s_add_u32 s38, s38, 0x40080
	v_lshl_add_u64 v[202:203], v[206:207], 0, s[16:17]
	s_addc_u32 s39, s39, 0
	s_add_i32 s40, s59, s48
	global_load_lds_dwordx4 v[202:203], off
	v_lshl_add_u64 v[202:203], s[38:39], 0, v[164:165]
	s_mov_b32 m0, s40
	s_nop 0
	global_load_lds_dwordx4 v[202:203], off
	v_lshl_add_u64 v[202:203], s[38:39], 0, v[168:169]
	s_add_i32 m0, s40, 0x2000
	s_nop 0
	global_load_lds_dwordx4 v[202:203], off
	v_lshl_add_u64 v[202:203], v[210:211], 0, s[16:17]
	s_mov_b32 m0, s73
	s_nop 0
	global_load_lds_dwordx4 v[202:203], off
	v_lshl_add_u64 v[202:203], v[214:215], 0, s[16:17]
	s_mov_b32 m0, s74
	s_nop 0
	global_load_lds_dwordx4 v[202:203], off
	s_waitcnt vmcnt(8)
	s_waitcnt lgkmcnt(0)
	s_barrier
	s_setprio 1
	s_waitcnt lgkmcnt(0)
	v_mfma_f32_16x16x32_bf16 v[62:65], v[130:133], v[178:181], v[62:65]
	v_mfma_f32_16x16x32_bf16 v[58:61], v[138:141], v[178:181], v[58:61]
	v_mfma_f32_16x16x32_bf16 v[46:49], v[130:133], v[186:189], v[46:49]
	v_mfma_f32_16x16x32_bf16 v[42:45], v[138:141], v[186:189], v[42:45]
	v_mfma_f32_16x16x32_bf16 v[30:33], v[130:133], v[218:221], v[30:33]
	v_mfma_f32_16x16x32_bf16 v[26:29], v[138:141], v[218:221], v[26:29]
	v_mfma_f32_16x16x32_bf16 v[22:25], v[130:133], v[226:229], v[22:25]
	v_mfma_f32_16x16x32_bf16 v[10:13], v[138:141], v[226:229], v[10:13]
	v_mfma_f32_16x16x32_bf16 v[62:65], v[134:137], v[182:185], v[62:65]
	v_mfma_f32_16x16x32_bf16 v[58:61], v[142:145], v[182:185], v[58:61]
	v_mfma_f32_16x16x32_bf16 v[46:49], v[134:137], v[190:193], v[46:49]
	v_mfma_f32_16x16x32_bf16 v[42:45], v[142:145], v[190:193], v[42:45]
	v_mfma_f32_16x16x32_bf16 v[30:33], v[134:137], v[222:225], v[30:33]
	v_mfma_f32_16x16x32_bf16 v[26:29], v[142:145], v[222:225], v[26:29]
	v_mfma_f32_16x16x32_bf16 v[22:25], v[134:137], v[230:233], v[22:25]
	v_mfma_f32_16x16x32_bf16 v[10:13], v[142:145], v[230:233], v[10:13]
	s_setprio 0
	s_setprio 1
	v_mfma_f32_16x16x32_bf16 v[54:57], v[146:149], v[178:181], v[54:57]
	v_mfma_f32_16x16x32_bf16 v[50:53], v[154:157], v[178:181], v[50:53]
	v_mfma_f32_16x16x32_bf16 v[38:41], v[146:149], v[186:189], v[38:41]
	v_mfma_f32_16x16x32_bf16 v[34:37], v[154:157], v[186:189], v[34:37]
	v_mfma_f32_16x16x32_bf16 v[18:21], v[146:149], v[218:221], v[18:21]
	v_mfma_f32_16x16x32_bf16 v[14:17], v[154:157], v[218:221], v[14:17]
	v_mfma_f32_16x16x32_bf16 v[6:9], v[146:149], v[226:229], v[6:9]
	v_mfma_f32_16x16x32_bf16 v[2:5], v[154:157], v[226:229], v[2:5]
	v_mfma_f32_16x16x32_bf16 v[54:57], v[150:153], v[182:185], v[54:57]
	v_mfma_f32_16x16x32_bf16 v[50:53], v[158:161], v[182:185], v[50:53]
	v_mfma_f32_16x16x32_bf16 v[38:41], v[150:153], v[190:193], v[38:41]
	v_mfma_f32_16x16x32_bf16 v[34:37], v[158:161], v[190:193], v[34:37]
	v_mfma_f32_16x16x32_bf16 v[18:21], v[150:153], v[222:225], v[18:21]
	v_mfma_f32_16x16x32_bf16 v[14:17], v[158:161], v[222:225], v[14:17]
	v_mfma_f32_16x16x32_bf16 v[6:9], v[150:153], v[230:233], v[6:9]
	v_mfma_f32_16x16x32_bf16 v[2:5], v[158:161], v[230:233], v[2:5]
	s_setprio 0
	s_barrier
	s_add_i32 s35, s35, 2
	s_add_u32 s36, s36, 0x100
	s_addc_u32 s37, s37, 0
	s_add_u32 s23, s23, 0x100
	s_addc_u32 s25, s25, 0
	s_cmp_gt_u32 s35, 13
